# deferred out-proj sample tiles: producers write back L2 and count the tile, FFN-in waits on the count before staging its first sample-panel tile
# baseline (speedup 1.0000x reference)
.Lp3_pass2_done:
	s_and_saveexec_b64 s[0:1], s[96:97]
	s_cbranch_execz .Lp3_pass2_skip
	buffer_wbl2 sc1
	s_waitcnt vmcnt(0)
	v_mov_b32_e32 v2, 0
	v_mov_b32_e32 v3, 1
	global_atomic_add v2, v3, s[80:81] offset:32
.Lp3_pass2_skip:
	s_or_b64 exec, exec, s[0:1]
.Lp4_entry:
	s_add_u32 s8, s80, 0x9a08800
	s_addc_u32 s9, s81, 0
	v_mov_b32_e32 v11, v0
	s_cmpk_lt_i32 s2, 0x1616
	s_nop 0
	v_readfirstlane_b32 s5, v11
	s_cbranch_scc0 .LBB0_613
	v_lshlrev_b32_e32 v1, 4, v11
	v_add_u32_e32 v2, 0x2000, v1
	v_ashrrev_i32_e32 v3, 31, v2
	v_lshrrev_b32_e32 v3, 22, v3
	v_add_u32_e32 v3, v2, v3
	v_ashrrev_i32_e32 v10, 10, v3
	v_mul_i32_i24_e32 v3, 0x400, v10
	v_sub_u32_e32 v2, v2, v3
	v_lshrrev_b32_e32 v3, 4, v2
	v_bitop3_b32 v2, v3, v2, 32 bitop3:0x6c
	v_ashrrev_i32_e32 v3, 31, v2
	v_lshrrev_b32_e32 v3, 26, v3
	v_add_u32_e32 v3, v2, v3
	v_lshlrev_b32_e32 v4, 3, v10
	v_ashrrev_i32_e32 v12, 6, v3
	v_and_b32_e32 v4, -16, v4
	v_add_u32_e32 v4, v12, v4
	v_and_b32_e32 v5, 3, v12
	s_mov_b32 s0, 0x1fffe0
	v_lshrrev_b32_e32 v6, 2, v4
	v_lshlrev_b32_e32 v7, 1, v4
	v_and_b32_e32 v3, 0xc0, v3
	v_and_or_b32 v5, v4, s0, v5
	v_and_b32_e32 v6, 4, v6
	v_and_b32_e32 v7, 24, v7
	v_sub_u32_e32 v2, v2, v3
	v_mov_b32_e32 v3, 1
	v_or3_b32 v5, v5, v6, v7
	v_lshlrev_b32_e32 v6, 5, v10
	v_ashrrev_i16_sdwa v2, v3, sext(v2) dst_sel:DWORD dst_unused:UNUSED_PAD src0_sel:DWORD src1_sel:BYTE_0
	v_and_b32_e32 v6, 32, v6
	v_bfe_i32 v13, v2, 0, 16
	v_add_lshl_u32 v2, v6, v13, 1
	v_lshl_add_u32 v130, v5, 11, v2
	s_waitcnt vmcnt(8)
	v_lshl_add_u32 v132, v4, 11, v2
	v_bfe_i32 v2, v11, 27, 1
	v_lshrrev_b32_e32 v2, 22, v2
	v_add_u32_e32 v2, v1, v2
	v_and_b32_e32 v2, 0xfffffc00, v2
	v_sub_u32_e32 v1, v1, v2
	v_lshrrev_b32_e32 v2, 4, v1
	v_ashrrev_i32_e32 v4, 31, v11
	v_bitop3_b32 v1, v2, v1, 32 bitop3:0x6c
	v_lshrrev_b32_e32 v4, 26, v4
	v_ashrrev_i32_e32 v2, 31, v1
	v_add_u32_e32 v4, v11, v4
	v_lshrrev_b32_e32 v2, 26, v2
	v_ashrrev_i32_e32 v15, 6, v4
	v_add_u32_e32 v2, v1, v2
	v_lshlrev_b32_e32 v4, 3, v15
	v_ashrrev_i32_e32 v14, 6, v2
	v_and_b32_e32 v4, -16, v4
	s_add_u32 s3, s80, 0x888800
	v_add_u32_e32 v4, v14, v4
	v_and_b32_e32 v5, 3, v14
	s_addc_u32 s17, s81, 0
	v_and_or_b32 v5, v4, s0, v5
	s_lshr_b32 s0, s86, 29
	s_add_i32 s0, s2, s0
	s_ashr_i32 s1, s0, 3
	s_and_b32 s0, s0, -8
	s_sub_i32 s0, s2, s0
	s_ashr_i32 s12, s5, 6
	s_mul_i32 s6, s0, 0x2c2
	s_ashr_i32 s14, s5, 8
	s_lshl_b32 s19, s12, 10
	s_add_i32 s6, s6, 6
	s_mul_i32 s4, s0, 0x2c3
	s_cmp_lt_i32 s0, 6
	s_cselect_b32 s0, s4, s6
	s_add_i32 s0, s0, s1
	s_mul_hi_i32 s1, s0, 0x2e8ba2e9
	s_lshr_b32 s4, s1, 31
	s_ashr_i32 s1, s1, 4
	v_lshrrev_b32_e32 v6, 2, v4
	v_lshlrev_b32_e32 v7, 1, v4
	v_and_b32_e32 v2, 0xc0, v2
	s_add_i32 s1, s1, s4
	v_and_b32_e32 v6, 4, v6
	v_and_b32_e32 v7, 24, v7
	v_sub_u32_e32 v1, v1, v2
	s_lshl_b32 s6, s1, 2
	v_or3_b32 v5, v5, v6, v7
	v_lshlrev_b32_e32 v6, 5, v15
	v_ashrrev_i16_sdwa v1, v3, sext(v1) dst_sel:DWORD dst_unused:UNUSED_PAD src0_sel:DWORD src1_sel:BYTE_0
	s_sub_i32 s4, 0x101, s6
	v_and_b32_e32 v6, 32, v6
	v_bfe_i32 v16, v1, 0, 16
	s_min_u32 s7, s4, 4
	s_mulk_i32 s1, 0x58
	v_add_lshl_u32 v1, v6, v16, 1
	s_sub_i32 s13, s0, s1
	v_cvt_f32_ubyte0_e32 v3, s7
	v_lshl_add_u32 v134, v5, 11, v1
	v_cvt_f32_i32_e32 v2, s13
	v_rcp_iflag_f32_e32 v5, v3
	v_lshl_add_u32 v136, v4, 11, v1
	s_ashr_i32 s0, s13, 30
	s_or_b32 s4, s0, 1
	v_mul_f32_e32 v1, v2, v5
	v_trunc_f32_e32 v1, v1
	v_fma_f32 v2, -v1, v3, v2
	v_cvt_i32_f32_e32 v1, v1
	v_cmp_ge_f32_e64 s[0:1], |v2|, v3
	s_and_b64 s[0:1], s[0:1], exec
	s_cselect_b32 s0, s4, 0
	v_readfirstlane_b32 s1, v1
	s_add_i32 s4, s1, s0
	s_mul_i32 s0, s4, s7
	s_sub_i32 s0, s13, s0
	s_sext_i32_i8 s0, s0
	s_add_i32 s0, s6, s0
	s_ashr_i32 s1, s0, 31
	s_bfe_i64 s[20:21], s[4:5], 0x80000
	s_lshl_b64 s[6:7], s[0:1], 19
	s_lshl_b64 s[20:21], s[20:21], 19
	s_add_u32 s30, s3, s20
	s_addc_u32 s31, s17, s21
	s_add_i32 s44, s19, 0
	s_add_i32 m0, s44, 0x10000
	v_mov_b32_e32 v135, 0
	global_load_lds_dwordx4 v134, s[30:31]
	s_add_i32 m0, s44, 0x12000
	s_add_u32 s20, s30, 0x40000
	global_load_lds_dwordx4 v130, s[30:31]
	s_addc_u32 s21, s31, 0
	s_add_i32 m0, s44, 0x14000
	v_mov_b32_e32 v131, v135
	global_load_lds_dwordx4 v134, s[20:21]
	s_add_i32 m0, s44, 0x16000
	s_add_u32 s28, s40, s6
	s_addc_u32 s29, s41, s7
	s_add_i32 s45, s44, 0x2000
	global_load_lds_dwordx4 v130, s[20:21]
	s_mov_b32 m0, s44
	s_add_u32 s6, s28, 0x40000
	global_load_lds_dwordx4 v136, s[28:29]
	s_mov_b32 m0, s45
	s_addc_u32 s7, s29, 0
	s_add_i32 s33, s44, 0x4000
	global_load_lds_dwordx4 v132, s[28:29]
	s_mov_b32 m0, s33
	s_add_i32 s46, s44, 0x6000
	global_load_lds_dwordx4 v136, s[6:7]
	s_mov_b32 m0, s46
	v_mov_b32_e32 v137, v135
	global_load_lds_dwordx4 v132, s[6:7]
	v_mov_b32_e32 v133, v135
	s_cmp_eq_u32 s14, 1
	s_mov_b32 s47, 0
	v_lshl_add_u64 v[8:9], s[30:31], 0, v[134:135]
	v_lshl_add_u64 v[6:7], s[30:31], 0, v[130:131]
	v_lshl_add_u64 v[2:3], s[28:29], 0, v[136:137]
	s_cselect_b64 s[6:7], -1, 0
	s_cmp_lg_u32 s14, 1
	v_lshl_add_u64 v[4:5], s[28:29], 0, v[132:133]
	s_cbranch_scc1 .LBB0_596
	s_barrier

.LBB0_605:
	s_cmpk_lg_i32 s22, 0x100
	s_cbranch_scc1 .Lp4_nowait
	s_mov_b32 s101, 0
.Lp4_spin:
	v_mov_b32_e32 v2, 0
	global_load_dword v2, v2, s[80:81] offset:32 sc1
	s_waitcnt vmcnt(0)
	v_readfirstlane_b32 s100, v2
	s_cmp_ge_u32 s100, 4
	s_cbranch_scc1 .Lp4_ok
	s_add_u32 s101, s101, 1
	s_cmpk_gt_u32 s101, 0x4000
	s_cbranch_scc1 .Lp4_ok
	s_sleep 4
	s_branch .Lp4_spin
.Lp4_ok:
	buffer_inv sc1
.Lp4_nowait:
	s_ashr_i32 s23, s22, 31
	s_lshl_b64 s[24:25], s[22:23], 19
	s_add_u32 s24, s40, s24
	s_addc_u32 s25, s41, s25
	s_and_b64 s[26:27], s[4:5], exec
	s_cselect_b32 s23, s25, s29
	s_cselect_b32 s52, s24, s28
	s_ashr_i32 s21, s20, 31
	s_lshl_b64 s[26:27], s[20:21], 19
	s_add_u32 s26, s3, s26
	s_addc_u32 s27, s17, s27
	s_and_b64 s[38:39], s[4:5], exec
	s_cselect_b32 s21, s27, s31
	s_cselect_b32 s53, s26, s30
	s_cselect_b32 s38, s22, s0
	v_lshl_add_u32 v248, s38, 8, v1
	s_add_u32 s28, s28, 0x40080
	s_addc_u32 s29, s29, 0
	s_add_u32 s54, s30, 0x100
	s_addc_u32 s55, s31, 0
	s_mov_b32 s56, -2
	ds_read_b128 v[146:149], v154
	ds_read_b128 v[158:161], v154 offset:1024
	ds_read_b128 v[162:165], v154 offset:2048
	ds_read_b128 v[166:169], v154 offset:3072
	ds_read_b128 v[172:175], v155
	ds_read_b128 v[176:179], v155 offset:1024
	ds_read_b128 v[180:183], v155 offset:2048
	ds_read_b128 v[184:187], v155 offset:3072
	s_add_u32 s30, s28, 0xfffc0080
	s_addc_u32 s31, s29, -1
	s_cmp_eq_u32 s56, 12
	s_cselect_b32 s39, s23, s31
	s_cselect_b32 s38, s52, s30
	s_cselect_b32 s31, s21, s55
	s_cselect_b32 s30, s53, s54
	v_lshl_add_u64 v[150:151], s[28:29], 0, v[138:139]
	s_add_i32 m0, s44, 0xc000
	ds_read_b128 v[188:191], v156
	ds_read_b128 v[192:195], v156 offset:1024
	ds_read_b128 v[196:199], v156 offset:2048
	ds_read_b128 v[200:203], v156 offset:3072
	ds_read_b128 v[204:207], v156 offset:4096
	ds_read_b128 v[212:215], v156 offset:5120
	ds_read_b128 v[216:219], v156 offset:6144
	ds_read_b128 v[220:223], v156 offset:7168
	global_load_lds_dwordx4 v[150:151], off
	v_lshl_add_u64 v[150:151], s[28:29], 0, v[140:141]
	s_add_i32 m0, s44, 0xe000
	s_nop 0
	global_load_lds_dwordx4 v[150:151], off
	s_waitcnt vmcnt(22)
	s_waitcnt lgkmcnt(0)
	s_barrier
	s_setprio 1
	s_waitcnt lgkmcnt(0)
	v_mfma_f32_16x16x32_bf16 v[118:121], v[146:149], v[188:191], 0
	v_mfma_f32_16x16x32_bf16 v[126:129], v[162:165], v[188:191], 0
	v_mfma_f32_16x16x32_bf16 v[110:113], v[146:149], v[196:199], 0
	v_mfma_f32_16x16x32_bf16 v[106:109], v[162:165], v[196:199], 0
	v_mfma_f32_16x16x32_bf16 v[86:89], v[146:149], v[204:207], 0
	v_mfma_f32_16x16x32_bf16 v[94:97], v[162:165], v[204:207], 0
	v_mfma_f32_16x16x32_bf16 v[78:81], v[146:149], v[216:219], 0
	v_mfma_f32_16x16x32_bf16 v[74:77], v[162:165], v[216:219], 0
	v_mfma_f32_16x16x32_bf16 v[118:121], v[158:161], v[192:195], v[118:121]
	v_mfma_f32_16x16x32_bf16 v[126:129], v[166:169], v[192:195], v[126:129]
	v_mfma_f32_16x16x32_bf16 v[110:113], v[158:161], v[200:203], v[110:113]
	v_mfma_f32_16x16x32_bf16 v[106:109], v[166:169], v[200:203], v[106:109]
	v_mfma_f32_16x16x32_bf16 v[86:89], v[158:161], v[212:215], v[86:89]
	v_mfma_f32_16x16x32_bf16 v[94:97], v[166:169], v[212:215], v[94:97]
	v_mfma_f32_16x16x32_bf16 v[78:81], v[158:161], v[220:223], v[78:81]
	v_mfma_f32_16x16x32_bf16 v[74:77], v[166:169], v[220:223], v[74:77]
	s_setprio 0
	s_setprio 1
	v_mfma_f32_16x16x32_bf16 v[114:117], v[172:175], v[188:191], 0
	v_mfma_f32_16x16x32_bf16 v[122:125], v[180:183], v[188:191], 0
	v_mfma_f32_16x16x32_bf16 v[102:105], v[172:175], v[196:199], 0
	v_mfma_f32_16x16x32_bf16 v[98:101], v[180:183], v[196:199], 0
	v_mfma_f32_16x16x32_bf16 v[82:85], v[172:175], v[204:207], 0
	v_mfma_f32_16x16x32_bf16 v[90:93], v[180:183], v[204:207], 0
	v_mfma_f32_16x16x32_bf16 v[70:73], v[172:175], v[216:219], 0
	v_mfma_f32_16x16x32_bf16 v[66:69], v[180:183], v[216:219], 0
	v_mfma_f32_16x16x32_bf16 v[114:117], v[176:179], v[192:195], v[114:117]
	v_mfma_f32_16x16x32_bf16 v[122:125], v[184:187], v[192:195], v[122:125]
	v_mfma_f32_16x16x32_bf16 v[102:105], v[176:179], v[200:203], v[102:105]
	v_mfma_f32_16x16x32_bf16 v[98:101], v[184:187], v[200:203], v[98:101]
	v_mfma_f32_16x16x32_bf16 v[82:85], v[176:179], v[212:215], v[82:85]
	v_mfma_f32_16x16x32_bf16 v[90:93], v[184:187], v[212:215], v[90:93]
	v_mfma_f32_16x16x32_bf16 v[70:73], v[176:179], v[220:223], v[70:73]
	v_mfma_f32_16x16x32_bf16 v[66:69], v[184:187], v[220:223], v[66:69]
	s_setprio 0
	s_barrier
	s_add_i32 s42, s36, s19
	v_lshl_add_u64 v[150:151], s[30:31], 0, v[134:135]
	s_mov_b32 m0, s42
	ds_read_b128 v[188:191], v156 offset:16384
	ds_read_b128 v[192:195], v156 offset:17408
	ds_read_b128 v[196:199], v156 offset:18432
	ds_read_b128 v[200:203], v156 offset:19456
	ds_read_b128 v[204:207], v156 offset:20480
	ds_read_b128 v[212:215], v156 offset:21504
	ds_read_b128 v[216:219], v156 offset:22528
	ds_read_b128 v[220:223], v156 offset:23552
	global_load_lds_dwordx4 v[150:151], off
	s_add_i32 m0, s42, 0x2000
	s_add_u32 s42, s30, 0x40000
	v_lshl_add_u64 v[208:209], s[30:31], 0, v[130:131]
	s_addc_u32 s43, s31, 0
	s_add_i32 s57, s37, s19
	global_load_lds_dwordx4 v[208:209], off
	v_lshl_add_u64 v[224:225], s[42:43], 0, v[134:135]
	s_mov_b32 m0, s57
	v_lshl_add_u64 v[226:227], s[38:39], 0, v[132:133]
	global_load_lds_dwordx4 v[224:225], off
	v_lshl_add_u64 v[224:225], s[42:43], 0, v[130:131]
	s_add_i32 m0, s57, 0x2000
	s_nop 0
	global_load_lds_dwordx4 v[224:225], off
	v_lshl_add_u64 v[224:225], s[38:39], 0, v[136:137]
	s_mov_b32 m0, s44
	s_nop 0
	global_load_lds_dwordx4 v[224:225], off
	s_mov_b32 m0, s45
	s_nop 0
	global_load_lds_dwordx4 v[226:227], off
	s_waitcnt vmcnt(22)
	s_waitcnt lgkmcnt(0)
	s_barrier
	s_setprio 1
	s_waitcnt lgkmcnt(0)
	v_mfma_f32_16x16x32_bf16 v[58:61], v[146:149], v[188:191], 0
	v_mfma_f32_16x16x32_bf16 v[62:65], v[162:165], v[188:191], 0
	v_mfma_f32_16x16x32_bf16 v[46:49], v[146:149], v[196:199], 0
	v_mfma_f32_16x16x32_bf16 v[42:45], v[162:165], v[196:199], 0
	v_mfma_f32_16x16x32_bf16 v[22:25], v[146:149], v[204:207], 0
	v_mfma_f32_16x16x32_bf16 v[30:33], v[162:165], v[204:207], 0
	v_mfma_f32_16x16x32_bf16 v[14:17], v[146:149], v[216:219], 0
	v_mfma_f32_16x16x32_bf16 v[10:13], v[162:165], v[216:219], 0
	v_mfma_f32_16x16x32_bf16 v[58:61], v[158:161], v[192:195], v[58:61]
	v_mfma_f32_16x16x32_bf16 v[62:65], v[166:169], v[192:195], v[62:65]
	v_mfma_f32_16x16x32_bf16 v[46:49], v[158:161], v[200:203], v[46:49]
	v_mfma_f32_16x16x32_bf16 v[42:45], v[166:169], v[200:203], v[42:45]
	v_mfma_f32_16x16x32_bf16 v[22:25], v[158:161], v[212:215], v[22:25]
	v_mfma_f32_16x16x32_bf16 v[30:33], v[166:169], v[212:215], v[30:33]
	v_mfma_f32_16x16x32_bf16 v[14:17], v[158:161], v[220:223], v[14:17]
	v_mfma_f32_16x16x32_bf16 v[10:13], v[166:169], v[220:223], v[10:13]
	s_setprio 0
	s_setprio 1
	v_mfma_f32_16x16x32_bf16 v[50:53], v[172:175], v[188:191], 0
	v_mfma_f32_16x16x32_bf16 v[54:57], v[180:183], v[188:191], 0
	v_mfma_f32_16x16x32_bf16 v[38:41], v[172:175], v[196:199], 0
	v_mfma_f32_16x16x32_bf16 v[34:37], v[180:183], v[196:199], 0
	v_mfma_f32_16x16x32_bf16 v[18:21], v[172:175], v[204:207], 0
	v_mfma_f32_16x16x32_bf16 v[26:29], v[180:183], v[204:207], 0
	v_mfma_f32_16x16x32_bf16 v[6:9], v[172:175], v[216:219], 0
	v_mfma_f32_16x16x32_bf16 v[2:5], v[180:183], v[216:219], 0
	v_mfma_f32_16x16x32_bf16 v[50:53], v[176:179], v[192:195], v[50:53]
	v_mfma_f32_16x16x32_bf16 v[54:57], v[184:187], v[192:195], v[54:57]
	v_mfma_f32_16x16x32_bf16 v[38:41], v[176:179], v[200:203], v[38:41]
	v_mfma_f32_16x16x32_bf16 v[34:37], v[184:187], v[200:203], v[34:37]
	v_mfma_f32_16x16x32_bf16 v[18:21], v[176:179], v[212:215], v[18:21]
	v_mfma_f32_16x16x32_bf16 v[26:29], v[184:187], v[212:215], v[26:29]
	v_mfma_f32_16x16x32_bf16 v[6:9], v[176:179], v[220:223], v[6:9]
	v_mfma_f32_16x16x32_bf16 v[2:5], v[184:187], v[220:223], v[2:5]
	s_setprio 0
	s_barrier
	s_add_i32 s42, 0, 0x18000
	v_add_u32_e32 v157, s42, v152
	s_add_i32 s43, 0, 0x1c000
	ds_read_b128 v[146:149], v157
	ds_read_b128 v[158:161], v157 offset:1024
	ds_read_b128 v[162:165], v157 offset:2048
	ds_read_b128 v[166:169], v157 offset:3072
	v_add_u32_e32 v157, s43, v152
	ds_read_b128 v[172:175], v157
	ds_read_b128 v[176:179], v157 offset:1024
	ds_read_b128 v[180:183], v157 offset:2048
	ds_read_b128 v[184:187], v157 offset:3072
	s_add_u32 s38, s38, 0x40000
	s_addc_u32 s39, s39, 0
	s_mov_b32 m0, s33
	v_lshl_add_u64 v[228:229], s[38:39], 0, v[136:137]
	ds_read_b128 v[188:191], v156 offset:32768
	ds_read_b128 v[192:195], v156 offset:33792
	ds_read_b128 v[196:199], v156 offset:34816
	ds_read_b128 v[200:203], v156 offset:35840
	ds_read_b128 v[204:207], v156 offset:36864
	ds_read_b128 v[212:215], v156 offset:37888
	ds_read_b128 v[216:219], v156 offset:38912
	ds_read_b128 v[220:223], v156 offset:39936
	global_load_lds_dwordx4 v[228:229], off
	v_lshl_add_u64 v[228:229], s[38:39], 0, v[132:133]
	s_mov_b32 m0, s46
	s_nop 0
	global_load_lds_dwordx4 v[228:229], off
	s_waitcnt vmcnt(8)
	s_waitcnt lgkmcnt(0)
	s_barrier
	s_setprio 1
	s_waitcnt lgkmcnt(0)
	v_mfma_f32_16x16x32_bf16 v[118:121], v[146:149], v[188:191], v[118:121]
	v_mfma_f32_16x16x32_bf16 v[126:129], v[162:165], v[188:191], v[126:129]
	v_mfma_f32_16x16x32_bf16 v[110:113], v[146:149], v[196:199], v[110:113]
	v_mfma_f32_16x16x32_bf16 v[106:109], v[162:165], v[196:199], v[106:109]
	v_mfma_f32_16x16x32_bf16 v[86:89], v[146:149], v[204:207], v[86:89]
	v_mfma_f32_16x16x32_bf16 v[94:97], v[162:165], v[204:207], v[94:97]
	v_mfma_f32_16x16x32_bf16 v[78:81], v[146:149], v[216:219], v[78:81]
	v_mfma_f32_16x16x32_bf16 v[74:77], v[162:165], v[216:219], v[74:77]
	v_mfma_f32_16x16x32_bf16 v[118:121], v[158:161], v[192:195], v[118:121]
	v_mfma_f32_16x16x32_bf16 v[126:129], v[166:169], v[192:195], v[126:129]
	v_mfma_f32_16x16x32_bf16 v[110:113], v[158:161], v[200:203], v[110:113]
	v_mfma_f32_16x16x32_bf16 v[106:109], v[166:169], v[200:203], v[106:109]
	v_mfma_f32_16x16x32_bf16 v[86:89], v[158:161], v[212:215], v[86:89]
	v_mfma_f32_16x16x32_bf16 v[94:97], v[166:169], v[212:215], v[94:97]
	v_mfma_f32_16x16x32_bf16 v[78:81], v[158:161], v[220:223], v[78:81]
	v_mfma_f32_16x16x32_bf16 v[74:77], v[166:169], v[220:223], v[74:77]
	s_setprio 0
	s_setprio 1
	v_mfma_f32_16x16x32_bf16 v[114:117], v[172:175], v[188:191], v[114:117]
	v_mfma_f32_16x16x32_bf16 v[122:125], v[180:183], v[188:191], v[122:125]
	v_mfma_f32_16x16x32_bf16 v[102:105], v[172:175], v[196:199], v[102:105]
	v_mfma_f32_16x16x32_bf16 v[98:101], v[180:183], v[196:199], v[98:101]
	v_mfma_f32_16x16x32_bf16 v[82:85], v[172:175], v[204:207], v[82:85]
	v_mfma_f32_16x16x32_bf16 v[90:93], v[180:183], v[204:207], v[90:93]
	v_mfma_f32_16x16x32_bf16 v[70:73], v[172:175], v[216:219], v[70:73]
	v_mfma_f32_16x16x32_bf16 v[66:69], v[180:183], v[216:219], v[66:69]
	v_mfma_f32_16x16x32_bf16 v[114:117], v[176:179], v[192:195], v[114:117]
	v_mfma_f32_16x16x32_bf16 v[122:125], v[184:187], v[192:195], v[122:125]
	v_mfma_f32_16x16x32_bf16 v[102:105], v[176:179], v[200:203], v[102:105]
	v_mfma_f32_16x16x32_bf16 v[98:101], v[184:187], v[200:203], v[98:101]
	v_mfma_f32_16x16x32_bf16 v[82:85], v[176:179], v[212:215], v[82:85]
	v_mfma_f32_16x16x32_bf16 v[90:93], v[184:187], v[212:215], v[90:93]
	v_mfma_f32_16x16x32_bf16 v[70:73], v[176:179], v[220:223], v[70:73]
	v_mfma_f32_16x16x32_bf16 v[66:69], v[184:187], v[220:223], v[66:69]
	s_setprio 0
	s_barrier
	s_add_i32 s38, s42, s19
	v_lshl_add_u64 v[150:151], v[150:151], 0, s[12:13]
	s_mov_b32 m0, s38
	ds_read_b128 v[188:191], v156 offset:49152
	ds_read_b128 v[192:195], v156 offset:50176
	ds_read_b128 v[196:199], v156 offset:51200
	ds_read_b128 v[200:203], v156 offset:52224
	ds_read_b128 v[204:207], v156 offset:53248
	ds_read_b128 v[212:215], v156 offset:54272
	ds_read_b128 v[216:219], v156 offset:55296
	ds_read_b128 v[220:223], v156 offset:56320
	global_load_lds_dwordx4 v[150:151], off
	s_add_i32 m0, s38, 0x2000
	s_add_u32 s30, s30, 0x40080
	v_lshl_add_u64 v[150:151], v[208:209], 0, s[12:13]
	s_addc_u32 s31, s31, 0
	s_add_i32 s38, s43, s19
	global_load_lds_dwordx4 v[150:151], off
	v_lshl_add_u64 v[150:151], s[30:31], 0, v[134:135]
	s_mov_b32 m0, s38
	s_nop 0
	global_load_lds_dwordx4 v[150:151], off
	v_lshl_add_u64 v[150:151], s[30:31], 0, v[130:131]
	s_add_i32 m0, s38, 0x2000
	s_nop 0
	global_load_lds_dwordx4 v[150:151], off
	v_lshl_add_u64 v[150:151], v[224:225], 0, s[12:13]
	s_mov_b32 m0, s48
	s_nop 0
	global_load_lds_dwordx4 v[150:151], off
	v_lshl_add_u64 v[150:151], v[226:227], 0, s[12:13]
	s_mov_b32 m0, s49
	s_nop 0
	global_load_lds_dwordx4 v[150:151], off
	s_waitcnt vmcnt(8)
	s_waitcnt lgkmcnt(0)
	s_barrier
	s_setprio 1
	s_waitcnt lgkmcnt(0)
	v_mfma_f32_16x16x32_bf16 v[58:61], v[146:149], v[188:191], v[58:61]
	v_mfma_f32_16x16x32_bf16 v[62:65], v[162:165], v[188:191], v[62:65]
	v_mfma_f32_16x16x32_bf16 v[46:49], v[146:149], v[196:199], v[46:49]
	v_mfma_f32_16x16x32_bf16 v[42:45], v[162:165], v[196:199], v[42:45]
	v_mfma_f32_16x16x32_bf16 v[22:25], v[146:149], v[204:207], v[22:25]
	v_mfma_f32_16x16x32_bf16 v[30:33], v[162:165], v[204:207], v[30:33]
	v_mfma_f32_16x16x32_bf16 v[14:17], v[146:149], v[216:219], v[14:17]
	v_mfma_f32_16x16x32_bf16 v[10:13], v[162:165], v[216:219], v[10:13]
	v_mfma_f32_16x16x32_bf16 v[58:61], v[158:161], v[192:195], v[58:61]
	v_mfma_f32_16x16x32_bf16 v[62:65], v[166:169], v[192:195], v[62:65]
	v_mfma_f32_16x16x32_bf16 v[46:49], v[158:161], v[200:203], v[46:49]
	v_mfma_f32_16x16x32_bf16 v[42:45], v[166:169], v[200:203], v[42:45]
	v_mfma_f32_16x16x32_bf16 v[22:25], v[158:161], v[212:215], v[22:25]
	v_mfma_f32_16x16x32_bf16 v[30:33], v[166:169], v[212:215], v[30:33]
	v_mfma_f32_16x16x32_bf16 v[14:17], v[158:161], v[220:223], v[14:17]
	v_mfma_f32_16x16x32_bf16 v[10:13], v[166:169], v[220:223], v[10:13]
	s_setprio 0
	s_setprio 1
	v_mfma_f32_16x16x32_bf16 v[50:53], v[172:175], v[188:191], v[50:53]
	v_mfma_f32_16x16x32_bf16 v[54:57], v[180:183], v[188:191], v[54:57]
	v_mfma_f32_16x16x32_bf16 v[38:41], v[172:175], v[196:199], v[38:41]
	v_mfma_f32_16x16x32_bf16 v[34:37], v[180:183], v[196:199], v[34:37]
	v_mfma_f32_16x16x32_bf16 v[18:21], v[172:175], v[204:207], v[18:21]
	v_mfma_f32_16x16x32_bf16 v[26:29], v[180:183], v[204:207], v[26:29]
	v_mfma_f32_16x16x32_bf16 v[6:9], v[172:175], v[216:219], v[6:9]
	v_mfma_f32_16x16x32_bf16 v[2:5], v[180:183], v[216:219], v[2:5]
	v_mfma_f32_16x16x32_bf16 v[50:53], v[176:179], v[192:195], v[50:53]
	v_mfma_f32_16x16x32_bf16 v[54:57], v[184:187], v[192:195], v[54:57]
	v_mfma_f32_16x16x32_bf16 v[38:41], v[176:179], v[200:203], v[38:41]
	v_mfma_f32_16x16x32_bf16 v[34:37], v[184:187], v[200:203], v[34:37]
	v_mfma_f32_16x16x32_bf16 v[18:21], v[176:179], v[212:215], v[18:21]
	v_mfma_f32_16x16x32_bf16 v[26:29], v[184:187], v[212:215], v[26:29]
	v_mfma_f32_16x16x32_bf16 v[6:9], v[176:179], v[220:223], v[6:9]
	v_mfma_f32_16x16x32_bf16 v[2:5], v[184:187], v[220:223], v[2:5]
	s_setprio 0
	s_barrier
	s_add_i32 s56, s56, 2
	s_add_u32 s28, s28, 0x100
	s_addc_u32 s29, s29, 0
	s_add_u32 s54, s54, 0x100
	s_addc_u32 s55, s55, 0
